# P2a v_transpose rewritten: the V rows of all 8 units per workgroup loaded up front, no per-unit vmcnt(0) drain
# speedup vs baseline: 1.0095x; 1.0095x over previous
.LBB0_263:
	v_mov_b32_e32 v0, v196
	s_and_b64 vcc, exec, s[38:39]
	s_cbranch_vccnz .LBB0_270
	v_lshrrev_b32_e32 v2, 3, v0
	v_and_b32_e32 v3, 7, v0
	v_mul_u32_u24_e64 v4, v2, s75
	v_mul_u32_u24_e32 v5, 0x90, v2
	v_mul_u32_u24_e32 v6, 0x480, v3
	v_lshlrev_b32_e32 v7, 14, v2
	v_lshl_add_u32 v4, v3, 4, v4
	v_lshl_add_u32 v5, v3, 4, v5
	v_lshl_add_u32 v6, v2, 1, v6
	v_lshl_add_u32 v7, v3, 4, v7
	s_lshr_b32 s0, s22, 7
	s_and_b32 s1, s22, 0x7f
	s_lshl_b32 s2, s1, 6
	s_add_i32 s3, s0, 0
	s_lshr_b32 s4, s3, 2
	s_and_b32 s5, s3, 3
	s_lshl_b32 s4, s4, 13
	s_add_i32 s4, s4, s2
	s_mul_i32 s4, s4, 0x1e00
	s_lshl_b32 s5, s5, 7
	s_add_i32 s4, s4, s5
	s_add_u32 s6, s36, s4
	s_addc_u32 s7, s37, 0
	global_load_dwordx4 v[44:47], v4, s[6:7] offset:3072
	s_add_i32 s3, s0, 2
	s_lshr_b32 s4, s3, 2
	s_and_b32 s5, s3, 3
	s_lshl_b32 s4, s4, 13
	s_add_i32 s4, s4, s2
	s_mul_i32 s4, s4, 0x1e00
	s_lshl_b32 s5, s5, 7
	s_add_i32 s4, s4, s5
	s_add_u32 s6, s36, s4
	s_addc_u32 s7, s37, 0
	global_load_dwordx4 v[48:51], v4, s[6:7] offset:3072
	s_add_i32 s3, s0, 4
	s_lshr_b32 s4, s3, 2
	s_and_b32 s5, s3, 3
	s_lshl_b32 s4, s4, 13
	s_add_i32 s4, s4, s2
	s_mul_i32 s4, s4, 0x1e00
	s_lshl_b32 s5, s5, 7
	s_add_i32 s4, s4, s5
	s_add_u32 s6, s36, s4
	s_addc_u32 s7, s37, 0
	global_load_dwordx4 v[52:55], v4, s[6:7] offset:3072
	s_add_i32 s3, s0, 6
	s_lshr_b32 s4, s3, 2
	s_and_b32 s5, s3, 3
	s_lshl_b32 s4, s4, 13
	s_add_i32 s4, s4, s2
	s_mul_i32 s4, s4, 0x1e00
	s_lshl_b32 s5, s5, 7
	s_add_i32 s4, s4, s5
	s_add_u32 s6, s36, s4
	s_addc_u32 s7, s37, 0
	global_load_dwordx4 v[56:59], v4, s[6:7] offset:3072
	s_add_i32 s3, s0, 8
	s_lshr_b32 s4, s3, 2
	s_and_b32 s5, s3, 3
	s_lshl_b32 s4, s4, 13
	s_add_i32 s4, s4, s2
	s_mul_i32 s4, s4, 0x1e00
	s_lshl_b32 s5, s5, 7
	s_add_i32 s4, s4, s5
	s_add_u32 s6, s36, s4
	s_addc_u32 s7, s37, 0
	global_load_dwordx4 v[60:63], v4, s[6:7] offset:3072
	s_add_i32 s3, s0, 10
	s_lshr_b32 s4, s3, 2
	s_and_b32 s5, s3, 3
	s_lshl_b32 s4, s4, 13
	s_add_i32 s4, s4, s2
	s_mul_i32 s4, s4, 0x1e00
	s_lshl_b32 s5, s5, 7
	s_add_i32 s4, s4, s5
	s_add_u32 s6, s36, s4
	s_addc_u32 s7, s37, 0
	global_load_dwordx4 v[64:67], v4, s[6:7] offset:3072
	s_add_i32 s3, s0, 12
	s_lshr_b32 s4, s3, 2
	s_and_b32 s5, s3, 3
	s_lshl_b32 s4, s4, 13
	s_add_i32 s4, s4, s2
	s_mul_i32 s4, s4, 0x1e00
	s_lshl_b32 s5, s5, 7
	s_add_i32 s4, s4, s5
	s_add_u32 s6, s36, s4
	s_addc_u32 s7, s37, 0
	global_load_dwordx4 v[68:71], v4, s[6:7] offset:3072
	s_add_i32 s3, s0, 14
	s_lshr_b32 s4, s3, 2
	s_and_b32 s5, s3, 3
	s_lshl_b32 s4, s4, 13
	s_add_i32 s4, s4, s2
	s_mul_i32 s4, s4, 0x1e00
	s_lshl_b32 s5, s5, 7
	s_add_i32 s4, s4, s5
	s_add_u32 s6, s36, s4
	s_addc_u32 s7, s37, 0
	global_load_dwordx4 v[72:75], v4, s[6:7] offset:3072
	v_readlane_b32 s8, v252, 38
	v_readlane_b32 s9, v252, 39
	s_lshl_b32 s10, s1, 7
	s_waitcnt vmcnt(0)
	ds_write_b128 v5, v[44:47]
	s_waitcnt lgkmcnt(0)
	s_barrier
	ds_read_u16 v22, v6
	ds_read_u16 v23, v6 offset:144
	ds_read_u16 v24, v6 offset:288
	ds_read_u16 v25, v6 offset:432
	ds_read_u16 v26, v6 offset:576
	ds_read_u16 v27, v6 offset:720
	ds_read_u16 v28, v6 offset:864
	ds_read_u16 v29, v6 offset:1008
	s_add_i32 s3, s0, 0
	s_lshl_b32 s3, s3, 20
	s_add_i32 s3, s3, s10
	s_add_u32 s6, s8, s3
	s_addc_u32 s7, s9, 0
	s_waitcnt lgkmcnt(0)
	v_lshl_or_b32 v76, v23, 16, v22
	v_lshl_or_b32 v77, v25, 16, v24
	v_lshl_or_b32 v78, v27, 16, v26
	v_lshl_or_b32 v79, v29, 16, v28
	global_store_dwordx4 v7, v[76:79], s[6:7]
	ds_write_b128 v5, v[48:51] offset:9216
	s_waitcnt lgkmcnt(0)
	s_barrier
	ds_read_u16 v22, v6 offset:9216
	ds_read_u16 v23, v6 offset:9360
	ds_read_u16 v24, v6 offset:9504
	ds_read_u16 v25, v6 offset:9648
	ds_read_u16 v26, v6 offset:9792
	ds_read_u16 v27, v6 offset:9936
	ds_read_u16 v28, v6 offset:10080
	ds_read_u16 v29, v6 offset:10224
	s_add_i32 s3, s0, 2
	s_lshl_b32 s3, s3, 20
	s_add_i32 s3, s3, s10
	s_add_u32 s6, s8, s3
	s_addc_u32 s7, s9, 0
	s_waitcnt lgkmcnt(0)
	v_lshl_or_b32 v80, v23, 16, v22
	v_lshl_or_b32 v81, v25, 16, v24
	v_lshl_or_b32 v82, v27, 16, v26
	v_lshl_or_b32 v83, v29, 16, v28
	global_store_dwordx4 v7, v[80:83], s[6:7]
	ds_write_b128 v5, v[52:55]
	s_waitcnt lgkmcnt(0)
	s_barrier
	ds_read_u16 v22, v6
	ds_read_u16 v23, v6 offset:144
	ds_read_u16 v24, v6 offset:288
	ds_read_u16 v25, v6 offset:432
	ds_read_u16 v26, v6 offset:576
	ds_read_u16 v27, v6 offset:720
	ds_read_u16 v28, v6 offset:864
	ds_read_u16 v29, v6 offset:1008
	s_add_i32 s3, s0, 4
	s_lshl_b32 s3, s3, 20
	s_add_i32 s3, s3, s10
	s_add_u32 s6, s8, s3
	s_addc_u32 s7, s9, 0
	s_waitcnt lgkmcnt(0)
	v_lshl_or_b32 v84, v23, 16, v22
	v_lshl_or_b32 v85, v25, 16, v24
	v_lshl_or_b32 v86, v27, 16, v26
	v_lshl_or_b32 v87, v29, 16, v28
	global_store_dwordx4 v7, v[84:87], s[6:7]
	ds_write_b128 v5, v[56:59] offset:9216
	s_waitcnt lgkmcnt(0)
	s_barrier
	ds_read_u16 v22, v6 offset:9216
	ds_read_u16 v23, v6 offset:9360
	ds_read_u16 v24, v6 offset:9504
	ds_read_u16 v25, v6 offset:9648
	ds_read_u16 v26, v6 offset:9792
	ds_read_u16 v27, v6 offset:9936
	ds_read_u16 v28, v6 offset:10080
	ds_read_u16 v29, v6 offset:10224
	s_add_i32 s3, s0, 6
	s_lshl_b32 s3, s3, 20
	s_add_i32 s3, s3, s10
	s_add_u32 s6, s8, s3
	s_addc_u32 s7, s9, 0
	s_waitcnt lgkmcnt(0)
	v_lshl_or_b32 v88, v23, 16, v22
	v_lshl_or_b32 v89, v25, 16, v24
	v_lshl_or_b32 v90, v27, 16, v26
	v_lshl_or_b32 v91, v29, 16, v28
	global_store_dwordx4 v7, v[88:91], s[6:7]
	ds_write_b128 v5, v[60:63]
	s_waitcnt lgkmcnt(0)
	s_barrier
	ds_read_u16 v22, v6
	ds_read_u16 v23, v6 offset:144
	ds_read_u16 v24, v6 offset:288
	ds_read_u16 v25, v6 offset:432
	ds_read_u16 v26, v6 offset:576
	ds_read_u16 v27, v6 offset:720
	ds_read_u16 v28, v6 offset:864
	ds_read_u16 v29, v6 offset:1008
	s_add_i32 s3, s0, 8
	s_lshl_b32 s3, s3, 20
	s_add_i32 s3, s3, s10
	s_add_u32 s6, s8, s3
	s_addc_u32 s7, s9, 0
	s_waitcnt lgkmcnt(0)
	v_lshl_or_b32 v92, v23, 16, v22
	v_lshl_or_b32 v93, v25, 16, v24
	v_lshl_or_b32 v94, v27, 16, v26
	v_lshl_or_b32 v95, v29, 16, v28
	global_store_dwordx4 v7, v[92:95], s[6:7]
	ds_write_b128 v5, v[64:67] offset:9216
	s_waitcnt lgkmcnt(0)
	s_barrier
	ds_read_u16 v22, v6 offset:9216
	ds_read_u16 v23, v6 offset:9360
	ds_read_u16 v24, v6 offset:9504
	ds_read_u16 v25, v6 offset:9648
	ds_read_u16 v26, v6 offset:9792
	ds_read_u16 v27, v6 offset:9936
	ds_read_u16 v28, v6 offset:10080
	ds_read_u16 v29, v6 offset:10224
	s_add_i32 s3, s0, 10
	s_lshl_b32 s3, s3, 20
	s_add_i32 s3, s3, s10
	s_add_u32 s6, s8, s3
	s_addc_u32 s7, s9, 0
	s_waitcnt lgkmcnt(0)
	v_lshl_or_b32 v96, v23, 16, v22
	v_lshl_or_b32 v97, v25, 16, v24
	v_lshl_or_b32 v98, v27, 16, v26
	v_lshl_or_b32 v99, v29, 16, v28
	global_store_dwordx4 v7, v[96:99], s[6:7]
	ds_write_b128 v5, v[68:71]
	s_waitcnt lgkmcnt(0)
	s_barrier
	ds_read_u16 v22, v6
	ds_read_u16 v23, v6 offset:144
	ds_read_u16 v24, v6 offset:288
	ds_read_u16 v25, v6 offset:432
	ds_read_u16 v26, v6 offset:576
	ds_read_u16 v27, v6 offset:720
	ds_read_u16 v28, v6 offset:864
	ds_read_u16 v29, v6 offset:1008
	s_add_i32 s3, s0, 12
	s_lshl_b32 s3, s3, 20
	s_add_i32 s3, s3, s10
	s_add_u32 s6, s8, s3
	s_addc_u32 s7, s9, 0
	s_waitcnt lgkmcnt(0)
	v_lshl_or_b32 v100, v23, 16, v22
	v_lshl_or_b32 v101, v25, 16, v24
	v_lshl_or_b32 v102, v27, 16, v26
	v_lshl_or_b32 v103, v29, 16, v28
	global_store_dwordx4 v7, v[100:103], s[6:7]
	ds_write_b128 v5, v[72:75] offset:9216
	s_waitcnt lgkmcnt(0)
	s_barrier
	ds_read_u16 v22, v6 offset:9216
	ds_read_u16 v23, v6 offset:9360
	ds_read_u16 v24, v6 offset:9504
	ds_read_u16 v25, v6 offset:9648
	ds_read_u16 v26, v6 offset:9792
	ds_read_u16 v27, v6 offset:9936
	ds_read_u16 v28, v6 offset:10080
	ds_read_u16 v29, v6 offset:10224
	s_add_i32 s3, s0, 14
	s_lshl_b32 s3, s3, 20
	s_add_i32 s3, s3, s10
	s_add_u32 s6, s8, s3
	s_addc_u32 s7, s9, 0
	s_waitcnt lgkmcnt(0)
	v_lshl_or_b32 v104, v23, 16, v22
	v_lshl_or_b32 v105, v25, 16, v24
	v_lshl_or_b32 v106, v27, 16, v26
	v_lshl_or_b32 v107, v29, 16, v28
	global_store_dwordx4 v7, v[104:107], s[6:7]
